# attention loop: P-step order 0,2,1,3 so next-tile K fragment reads issue early; all LDS fragment reads re-timed
# speedup vs baseline: 1.0423x; 1.0048x over previous
; #define LAS __attribute__((address_space(3)))
; #define PG8_SCHED __builtin_amdgcn_sched_barrier(0)
; #define MFMA32(a, b, c) __builtin_amdgcn_mfma_f32_32x32x16_bf16((a), (b), (c), 0, 0, 0)
; #define ATT_LDK(ring) do { _Pragma("unroll") for (int kh = 0; kh < 2; ++kh) _Pragma("unroll") for (int ks = 0; ks < 4; ++ks) \
;     kf[kh][ks] = *(const LAS bf16x8*)(lds + (ring) * 16384 + kh * 4096 + koff[ks]); } while (0)
; DI void attn_item(const Params& p, const int item) {
;     ...
; #pragma unroll
;     for (int db = 0; db < 4; ++db)
; #pragma unroll
;       for (int s = 0; s < 2; ++s) vfB[db][s] = *(const LAS bf16x8*)(vb + db * 4096 + voff[s + 2]);
;     bf16x8 pfN[4];
; #pragma unroll
;     for (int s = 0; s < 2; ++s)
; #pragma unroll
;       for (int db = 0; db < 4; ++db) O[db] = MFMA32(vfA[db][s], pf[s], O[db]);
;     ATT_SM(0, pfN);
;     PG8_SCHED;
;     ATT_LDK(m2);
; #pragma unroll
;     for (int s = 0; s < 2; ++s)
; #pragma unroll
;       for (int db = 0; db < 4; ++db) O[db] = MFMA32(vfB[db][s], pf[s + 2], O[db]);
;     ATT_SM(1, pfN);
;     PG8_SCHED;
; #pragma unroll
;     for (int s = 0; s < 4; ++s) pf[s] = pfN[s];
.Latt_near_done:
	s_waitcnt lgkmcnt(15)
	v_mfma_f32_32x32x16_bf16 v[48:63], v[176:179], v[120:123], v[48:63]
	s_nop 1
	v_exp_f32_e32 v64, v64
	v_exp_f32_e32 v65, v65
	v_exp_f32_e32 v66, v66
	v_exp_f32_e32 v67, v67
	s_waitcnt lgkmcnt(14)
	v_mfma_f32_32x32x16_bf16 v[32:47], v[180:183], v[120:123], v[32:47]
	ds_read_b128 v[176:179], v235 offset:49152
	ds_read_b128 v[180:183], v235 offset:53248
	v_exp_f32_e32 v68, v68
	v_exp_f32_e32 v69, v69
	v_add_f32_e32 v231, v64, v231
	v_add_f32_e32 v231, v65, v231
	v_add_f32_e32 v231, v66, v231
	s_waitcnt lgkmcnt(13)
	v_mfma_f32_32x32x16_bf16 v[16:31], v[184:187], v[120:123], v[16:31]
	ds_read_b128 v[184:187], v235 offset:61440
	v_exp_f32_e32 v70, v70
	v_exp_f32_e32 v71, v71
	v_add_f32_e32 v231, v67, v231
	v_add_f32_e32 v231, v68, v231
	v_add_f32_e32 v231, v69, v231
	s_waitcnt lgkmcnt(13)
	v_mfma_f32_32x32x16_bf16 v[0:15], v[188:191], v[120:123], v[0:15]
	v_exp_f32_e32 v72, v72
	v_exp_f32_e32 v73, v73
	v_add_f32_e32 v231, v70, v231
	v_add_f32_e32 v231, v71, v231
	v_cvt_pk_bf16_f32 v120, v64, v65
	s_waitcnt lgkmcnt(6)
	v_mfma_f32_32x32x16_bf16 v[48:63], v[128:131], v[124:127], v[48:63]
	ds_read_b128 v[128:131], v240 offset:4096
	v_exp_f32_e32 v74, v74
	v_exp_f32_e32 v75, v75
	v_add_f32_e32 v231, v72, v231
	v_add_f32_e32 v231, v73, v231
	v_cvt_pk_bf16_f32 v121, v66, v67
	s_waitcnt lgkmcnt(6)
	v_mfma_f32_32x32x16_bf16 v[32:47], v[132:135], v[124:127], v[32:47]
	ds_read_b128 v[132:135], v240
	v_exp_f32_e32 v76, v76
	v_exp_f32_e32 v77, v77
	v_add_f32_e32 v231, v74, v231
	v_add_f32_e32 v231, v75, v231
	v_cvt_pk_bf16_f32 v122, v68, v69
	s_waitcnt lgkmcnt(6)
	v_mfma_f32_32x32x16_bf16 v[16:31], v[136:139], v[124:127], v[16:31]
	ds_read_b128 v[136:139], v239 offset:4096
	v_exp_f32_e32 v78, v78
	v_exp_f32_e32 v79, v79
	v_add_f32_e32 v231, v76, v231
	v_add_f32_e32 v231, v77, v231
	v_cvt_pk_bf16_f32 v123, v70, v71
	s_waitcnt lgkmcnt(6)
	v_mfma_f32_32x32x16_bf16 v[0:15], v[140:143], v[124:127], v[0:15]
	ds_read_b128 v[140:143], v239
	v_exp_f32_e32 v80, v80
	v_exp_f32_e32 v81, v81
	v_add_f32_e32 v231, v78, v231
	v_add_f32_e32 v231, v79, v231
	v_exp_f32_e32 v82, v82
	v_mfma_f32_32x32x16_bf16 v[48:63], v[172:175], v[112:115], v[48:63]
	ds_read_b128 v[172:175], v235 offset:57344
	s_mov_b32 s1, s26
	s_mov_b32 s26, s27
	s_mov_b32 s27, s25
	s_mov_b32 s25, s1
	s_add_i32 s28, s28, 1
	s_add_i32 s24, s24, 64
	v_exp_f32_e32 v83, v83
	v_exp_f32_e32 v84, v84
	v_add_f32_e32 v231, v80, v231
	v_add_f32_e32 v231, v81, v231
	v_exp_f32_e32 v85, v85
	v_mfma_f32_32x32x16_bf16 v[32:47], v[168:171], v[112:115], v[32:47]
	s_and_b64 s[0:1], s[8:9], exec
	s_cselect_b32 s0, s27, s25
	s_add_i32 s1, s4, s28
	s_lshl_b32 s0, s0, 14
	v_exp_f32_e32 v86, v86
	v_exp_f32_e32 v87, v87
	v_add_f32_e32 v231, v82, v231
	v_add_f32_e32 v231, v83, v231
	v_cvt_pk_bf16_f32 v124, v80, v81
	v_mfma_f32_32x32x16_bf16 v[16:31], v[164:167], v[112:115], v[16:31]
	s_min_u32 s1, s1, s20
	s_add_i32 s98, s18, s0
	s_mul_i32 s99, s1, s17
	s_lshl_b32 s1, s26, 14
	v_exp_f32_e32 v88, v88
	v_exp_f32_e32 v89, v89
	v_add_f32_e32 v231, v84, v231
	v_add_f32_e32 v231, v85, v231
	v_cvt_pk_bf16_f32 v125, v82, v83
	v_mfma_f32_32x32x16_bf16 v[0:15], v[160:163], v[112:115], v[0:15]
	v_add_u32_e32 v241, s1, v228
	v_add_u32_e32 v242, s1, v227
	v_add_u32_e32 v234, s1, v226
	v_add_u32_e32 v235, s1, v225
	v_exp_f32_e32 v90, v90
	v_exp_f32_e32 v91, v91
	v_add_f32_e32 v231, v86, v231
	v_add_f32_e32 v231, v87, v231
	v_cvt_pk_bf16_f32 v126, v84, v85
	v_cvt_pk_bf16_f32 v112, v72, v73
	s_waitcnt lgkmcnt(7)
	v_mfma_f32_32x32x16_bf16 v[48:63], v[176:179], v[116:119], v[48:63]
	s_add_i32 s29, s28, 1
	s_cmp_lt_i32 s29, s19
	s_cselect_b64 s[34:35], -1, 0
	s_cmp_ge_u32 s29, s21
	s_cselect_b64 s[30:31], -1, 0
	s_or_b64 s[34:35], s[34:35], s[30:31]
	s_lshl_b32 s1, s25, 14
	v_add_u32_e32 v237, s1, v220
	v_add_u32_e32 v238, s1, v221
	v_add_u32_e32 v239, s1, v222
	v_add_u32_e32 v240, s1, v223
	v_exp_f32_e32 v92, v92
	v_exp_f32_e32 v93, v93
	v_add_f32_e32 v231, v88, v231
	v_add_f32_e32 v231, v89, v231
	v_cvt_pk_bf16_f32 v127, v86, v87
	v_cvt_pk_bf16_f32 v113, v74, v75
	s_waitcnt lgkmcnt(6)
	v_mfma_f32_32x32x16_bf16 v[32:47], v[180:183], v[116:119], v[32:47]
	s_cmp_eq_u32 s19, s28
	s_cselect_b64 s[0:1], -1, 0
	s_and_b64 s[30:31], s[10:11], s[0:1]
	s_cmp_eq_u32 s5, s24
	s_cselect_b64 s[0:1], -1, 0
	s_or_b64 s[30:31], s[30:31], s[0:1]
	v_exp_f32_e32 v94, v94
	v_exp_f32_e32 v95, v95
	v_add_f32_e32 v231, v90, v231
	v_add_f32_e32 v231, v91, v231
	v_cvt_pk_bf16_f32 v114, v76, v77
	s_waitcnt lgkmcnt(0)
	v_mfma_f32_32x32x16_bf16 v[16:31], v[172:175], v[116:119], v[16:31]
	s_cmp_eq_u32 s22, s24
	s_cselect_b64 s[100:101], -1, 0
	v_add_f32_e32 v231, v92, v231
	v_add_f32_e32 v231, v93, v231
	v_add_f32_e32 v231, v94, v231
	v_add_f32_e32 v231, v95, v231
	v_cvt_pk_bf16_f32 v115, v78, v79
	v_mfma_f32_32x32x16_bf16 v[0:15], v[184:187], v[116:119], v[0:15]
	v_cvt_pk_bf16_f32 v116, v88, v89
	v_cvt_pk_bf16_f32 v117, v90, v91
	v_cvt_pk_bf16_f32 v118, v92, v93
	v_cvt_pk_bf16_f32 v119, v94, v95
	s_cmp_eq_u32 s20, s28
	s_cbranch_scc0 .LBB0_987
	s_branch .LBB0_995
